# third division pass: time-shared interleaved IEEE division chains in the LRU gate epilogue -> v_rcp_f32 (chain slots kept as s_nop)
# baseline (speedup 1.0000x reference)
.LBB0_310:
	s_or_b64 exec, exec, s[40:41]
	v_and_b32_e32 v67, 64, v210
	v_xor_b32_e32 v66, 32, v210
	v_add_u32_e32 v67, 64, v67
	v_cmp_lt_i32_e32 vcc, v66, v67
	s_nop 1
	v_cndmask_b32_e32 v66, v210, v66, vcc
	v_lshlrev_b32_e32 v66, 2, v66
	ds_bpermute_b32 v66, v66, v233
	v_cmp_lt_u32_e32 vcc, v226, v175
	s_and_saveexec_b64 s[4:5], vcc
	s_cbranch_execz .LBB0_312
	v_readlane_b32 s6, v254, 20
	v_lshlrev_b64 v[68:69], 11, v[0:1]
	v_readlane_b32 s7, v254, 21
	s_waitcnt lgkmcnt(0)
	v_add_f32_e32 v70, v233, v66
	v_lshlrev_b32_e32 v0, 11, v226
	v_lshl_add_u64 v[68:69], s[6:7], 0, v[68:69]
	s_nop 1
	v_lshl_add_u64 v[68:69], v[68:69], 0, v[0:1]
	v_lshl_add_u64 v[66:67], v[176:177], 1, v[68:69]
	v_lshlrev_b32_e32 v0, 1, v179
	v_lshl_add_u64 v[66:67], v[66:67], 0, v[0:1]
	s_nop 7
	v_rcp_f32_e32 v0, v70
	s_nop 0
	v_pk_mul_f32 v[34:35], v[34:35], v[0:1] op_sel_hi:[1,0]
	v_pk_mul_f32 v[36:37], v[36:37], v[0:1] op_sel_hi:[1,0]
	v_cvt_pk_bf16_f32 v34, v34, v35
	v_cvt_pk_bf16_f32 v35, v36, v37
	global_store_dwordx2 v[66:67], v[34:35], off
	v_pk_mul_f32 v[34:35], v[38:39], v[0:1] op_sel_hi:[1,0]
	v_pk_mul_f32 v[36:37], v[40:41], v[0:1] op_sel_hi:[1,0]
	v_cvt_pk_bf16_f32 v34, v34, v35
	v_cvt_pk_bf16_f32 v35, v36, v37
	global_store_dwordx2 v[66:67], v[34:35], off offset:16
	v_pk_mul_f32 v[34:35], v[42:43], v[0:1] op_sel_hi:[1,0]
	v_pk_mul_f32 v[36:37], v[44:45], v[0:1] op_sel_hi:[1,0]
	v_cvt_pk_bf16_f32 v34, v34, v35
	v_cvt_pk_bf16_f32 v35, v36, v37
	global_store_dwordx2 v[66:67], v[34:35], off offset:32
	v_pk_mul_f32 v[34:35], v[46:47], v[0:1] op_sel_hi:[1,0]
	v_pk_mul_f32 v[36:37], v[48:49], v[0:1] op_sel_hi:[1,0]
	v_cvt_pk_bf16_f32 v34, v34, v35
	v_cvt_pk_bf16_f32 v35, v36, v37
	global_store_dwordx2 v[66:67], v[34:35], off offset:48
	v_pk_mul_f32 v[34:35], v[50:51], v[0:1] op_sel_hi:[1,0]
	v_pk_mul_f32 v[36:37], v[52:53], v[0:1] op_sel_hi:[1,0]
	v_pk_mul_f32 v[18:19], v[18:19], v[0:1] op_sel_hi:[1,0]
	v_pk_mul_f32 v[20:21], v[20:21], v[0:1] op_sel_hi:[1,0]
	v_pk_mul_f32 v[2:3], v[2:3], v[0:1] op_sel_hi:[1,0]
	v_pk_mul_f32 v[4:5], v[4:5], v[0:1] op_sel_hi:[1,0]
	v_cvt_pk_bf16_f32 v34, v34, v35
	v_cvt_pk_bf16_f32 v35, v36, v37
	v_cvt_pk_bf16_f32 v18, v18, v19
	v_cvt_pk_bf16_f32 v19, v20, v21
	v_cvt_pk_bf16_f32 v2, v2, v3
	v_cvt_pk_bf16_f32 v3, v4, v5
	global_store_dwordx2 v[66:67], v[34:35], off offset:64
	v_pk_mul_f32 v[34:35], v[54:55], v[0:1] op_sel_hi:[1,0]
	v_pk_mul_f32 v[36:37], v[56:57], v[0:1] op_sel_hi:[1,0]
	global_store_dwordx2 v[66:67], v[18:19], off offset:128
	v_pk_mul_f32 v[18:19], v[22:23], v[0:1] op_sel_hi:[1,0]
	v_pk_mul_f32 v[20:21], v[24:25], v[0:1] op_sel_hi:[1,0]
	global_store_dwordx2 v[66:67], v[2:3], off offset:192
	v_pk_mul_f32 v[2:3], v[6:7], v[0:1] op_sel_hi:[1,0]
	v_pk_mul_f32 v[4:5], v[8:9], v[0:1] op_sel_hi:[1,0]
	v_cvt_pk_bf16_f32 v34, v34, v35
	v_cvt_pk_bf16_f32 v35, v36, v37
	v_cvt_pk_bf16_f32 v18, v18, v19
	v_cvt_pk_bf16_f32 v19, v20, v21
	v_cvt_pk_bf16_f32 v2, v2, v3
	v_cvt_pk_bf16_f32 v3, v4, v5
	global_store_dwordx2 v[66:67], v[34:35], off offset:80
	v_pk_mul_f32 v[34:35], v[58:59], v[0:1] op_sel_hi:[1,0]
	v_pk_mul_f32 v[36:37], v[60:61], v[0:1] op_sel_hi:[1,0]
	global_store_dwordx2 v[66:67], v[18:19], off offset:144
	v_pk_mul_f32 v[18:19], v[26:27], v[0:1] op_sel_hi:[1,0]
	v_pk_mul_f32 v[20:21], v[28:29], v[0:1] op_sel_hi:[1,0]
	global_store_dwordx2 v[66:67], v[2:3], off offset:208
	v_pk_mul_f32 v[2:3], v[10:11], v[0:1] op_sel_hi:[1,0]
	v_pk_mul_f32 v[4:5], v[12:13], v[0:1] op_sel_hi:[1,0]
	v_cvt_pk_bf16_f32 v34, v34, v35
	v_cvt_pk_bf16_f32 v35, v36, v37
	v_cvt_pk_bf16_f32 v18, v18, v19
	v_cvt_pk_bf16_f32 v19, v20, v21
	v_cvt_pk_bf16_f32 v2, v2, v3
	v_cvt_pk_bf16_f32 v3, v4, v5
	global_store_dwordx2 v[66:67], v[34:35], off offset:96
	v_pk_mul_f32 v[34:35], v[62:63], v[0:1] op_sel_hi:[1,0]
	v_pk_mul_f32 v[36:37], v[64:65], v[0:1] op_sel_hi:[1,0]
	global_store_dwordx2 v[66:67], v[18:19], off offset:160
	v_pk_mul_f32 v[18:19], v[30:31], v[0:1] op_sel_hi:[1,0]
	v_pk_mul_f32 v[20:21], v[32:33], v[0:1] op_sel_hi:[1,0]
	global_store_dwordx2 v[66:67], v[2:3], off offset:224
	v_pk_mul_f32 v[2:3], v[14:15], v[0:1] op_sel_hi:[1,0]
	v_pk_mul_f32 v[4:5], v[16:17], v[0:1] op_sel_hi:[1,0]
	v_cvt_pk_bf16_f32 v34, v34, v35
	v_cvt_pk_bf16_f32 v35, v36, v37
	v_cvt_pk_bf16_f32 v18, v18, v19
	v_cvt_pk_bf16_f32 v19, v20, v21
	v_cvt_pk_bf16_f32 v2, v2, v3
	v_cvt_pk_bf16_f32 v3, v4, v5
	global_store_dwordx2 v[66:67], v[34:35], off offset:112
	global_store_dwordx2 v[66:67], v[18:19], off offset:176
	global_store_dwordx2 v[66:67], v[2:3], off offset:240

.LBB0_374:
	s_or_b64 exec, exec, s[26:27]
	s_waitcnt vmcnt(1) lgkmcnt(0)
	v_add_f32_e32 v76, v8, v76
	v_mul_f32_e32 v76, 0xbfb8aa3b, v76
	v_exp_f32_e32 v76, v76
	v_add_f32_e32 v77, v9, v77
	v_mul_f32_e32 v77, 0xbfb8aa3b, v77
	v_exp_f32_e32 v77, v77
	v_add_f32_e32 v76, 1.0, v76
	v_add_f32_e32 v77, 1.0, v77
	v_rcp_f32_e32 v76, v76
	s_nop 2
	v_add_f32_e32 v75, v7, v75
	v_mul_f32_e32 v75, 0xbfb8aa3b, v75
	v_mul_f32_e32 v76, v76, v97
	s_nop 0
	v_exp_f32_e32 v75, v75
	s_waitcnt vmcnt(0)
	v_lshlrev_b32_e32 v105, 16, v83
	s_nop 1
	v_mul_f32_e32 v76, v76, v105
	s_nop 2
	v_add_f32_e32 v75, 1.0, v75
	s_nop 3
	v_rcp_f32_e32 v77, v77
	s_nop 0
	v_mul_f32_e32 v97, 0x3fb8aa3b, v99
	v_exp_f32_e32 v109, v97
	s_nop 2
	v_add_f32_e32 v74, v6, v74
	s_nop 0
	v_mul_f32_e32 v74, 0xbfb8aa3b, v74
	s_nop 0
	v_exp_f32_e32 v74, v74
	s_nop 2
	v_rcp_f32_e32 v75, v75
	s_nop 0
	v_add_f32_e32 v74, 1.0, v74
	v_and_b32_e32 v97, 0xffff0000, v82
	v_mul_f32_e32 v75, v75, v96
	s_nop 0
	v_mul_f32_e32 v75, v75, v97
	s_nop 0
	v_mul_f32_e32 v80, 0x3fb8aa3b, v80
	v_exp_f32_e32 v108, v80
	v_lshlrev_b32_e32 v80, 16, v82
	s_nop 6
	v_mul_f32_e32 v79, 0x3fb8aa3b, v79
	v_mul_f32_e32 v78, 0x3fb8aa3b, v78
	s_nop 0
	v_exp_f32_e32 v107, v79
	v_exp_f32_e32 v106, v78
	v_rcp_f32_e32 v74, v74
	s_nop 0
	v_and_b32_e32 v79, 0xffff0000, v83
	v_mul_f32_e32 v77, v77, v81
	v_mul_f32_e32 v74, v74, v95
	v_mul_f32_e32 v77, v77, v79
	v_lshlrev_b64 v[78:79], 2, v[84:85]
	v_mul_f32_e32 v74, v74, v80
	v_lshl_add_u64 v[80:81], v[142:143], 0, v[78:79]
	v_lshl_add_u64 v[78:79], v[144:145], 0, v[78:79]
	global_store_dwordx4 v[80:81], v[106:109], off
	global_store_dwordx4 v[78:79], v[74:77], off

.LBB0_401:
	s_or_b64 exec, exec, s[26:27]
	s_waitcnt vmcnt(1) lgkmcnt(0)
	v_add_f32_e32 v76, v8, v76
	v_mul_f32_e32 v76, 0xbfb8aa3b, v76
	v_exp_f32_e32 v76, v76
	v_add_f32_e32 v77, v9, v77
	v_mul_f32_e32 v77, 0xbfb8aa3b, v77
	v_exp_f32_e32 v77, v77
	v_add_f32_e32 v76, 1.0, v76
	v_add_f32_e32 v77, 1.0, v77
	v_rcp_f32_e32 v76, v76
	s_nop 2
	v_add_f32_e32 v75, v7, v75
	v_mul_f32_e32 v75, 0xbfb8aa3b, v75
	v_mul_f32_e32 v76, v76, v99
	s_nop 0
	v_exp_f32_e32 v75, v75
	s_waitcnt vmcnt(0)
	v_lshlrev_b32_e32 v106, 16, v83
	s_nop 1
	v_mul_f32_e32 v76, v76, v106
	s_nop 2
	v_add_f32_e32 v75, 1.0, v75
	s_nop 3
	v_rcp_f32_e32 v77, v77
	s_nop 0
	v_mul_f32_e32 v99, 0x3fb8aa3b, v100
	v_exp_f32_e32 v109, v99
	s_nop 2
	v_add_f32_e32 v74, v6, v74
	s_nop 0
	v_mul_f32_e32 v74, 0xbfb8aa3b, v74
	s_nop 0
	v_exp_f32_e32 v74, v74
	s_nop 2
	v_rcp_f32_e32 v75, v75
	s_nop 0
	v_add_f32_e32 v74, 1.0, v74
	v_and_b32_e32 v99, 0xffff0000, v82
	v_mul_f32_e32 v75, v75, v97
	s_nop 0
	v_mul_f32_e32 v75, v75, v99
	s_nop 0
	v_mul_f32_e32 v80, 0x3fb8aa3b, v80
	v_exp_f32_e32 v108, v80
	v_lshlrev_b32_e32 v80, 16, v82
	s_nop 6
	v_mul_f32_e32 v79, 0x3fb8aa3b, v79
	v_mul_f32_e32 v78, 0x3fb8aa3b, v78
	s_nop 0
	v_exp_f32_e32 v107, v79
	v_exp_f32_e32 v106, v78
	v_rcp_f32_e32 v74, v74
	s_nop 0
	v_and_b32_e32 v79, 0xffff0000, v83
	v_mul_f32_e32 v77, v77, v81
	v_mul_f32_e32 v74, v74, v96
	v_mul_f32_e32 v77, v77, v79
	v_lshlrev_b64 v[78:79], 2, v[84:85]
	v_mul_f32_e32 v74, v74, v80
	v_lshl_add_u64 v[80:81], v[142:143], 0, v[78:79]
	v_lshl_add_u64 v[78:79], v[144:145], 0, v[78:79]
	global_store_dwordx4 v[80:81], v[106:109], off
	global_store_dwordx4 v[78:79], v[74:77], off

.LBB0_428:
	s_or_b64 exec, exec, s[26:27]
	s_waitcnt vmcnt(1) lgkmcnt(0)
	v_add_f32_e32 v12, v8, v12
	v_mul_f32_e32 v12, 0xbfb8aa3b, v12
	v_exp_f32_e32 v12, v12
	v_add_f32_e32 v13, v9, v13
	v_mul_f32_e32 v13, 0xbfb8aa3b, v13
	v_exp_f32_e32 v13, v13
	v_add_f32_e32 v12, 1.0, v12
	v_add_f32_e32 v13, 1.0, v13
	v_rcp_f32_e32 v12, v12
	s_nop 2
	v_add_f32_e32 v11, v7, v11
	v_mul_f32_e32 v12, v12, v23
	v_mul_f32_e32 v11, 0xbfb8aa3b, v11
	s_nop 0
	s_waitcnt vmcnt(0)
	v_lshlrev_b32_e32 v27, 16, v19
	s_nop 1
	v_exp_f32_e32 v11, v11
	v_mul_f32_e32 v12, v12, v27
	s_nop 3
	v_add_f32_e32 v11, 1.0, v11
	s_nop 2
	v_rcp_f32_e32 v13, v13
	s_nop 0
	v_mul_f32_e32 v23, 0x3fb8aa3b, v24
	v_exp_f32_e32 v25, v23
	s_nop 2
	v_add_f32_e32 v10, v6, v10
	s_nop 0
	v_mul_f32_e32 v10, 0xbfb8aa3b, v10
	s_nop 0
	v_exp_f32_e32 v10, v10
	s_nop 2
	v_rcp_f32_e32 v11, v11
	s_nop 0
	v_add_f32_e32 v10, 1.0, v10
	v_and_b32_e32 v23, 0xffff0000, v18
	v_mul_f32_e32 v11, v11, v22
	s_nop 0
	v_mul_f32_e32 v11, v11, v23
	s_nop 0
	v_mul_f32_e32 v16, 0x3fb8aa3b, v16
	v_exp_f32_e32 v24, v16
	v_lshlrev_b32_e32 v16, 16, v18
	s_nop 7
	v_rcp_f32_e32 v10, v10
	s_nop 0
	v_mul_f32_e32 v10, v10, v14
	v_mul_f32_e32 v14, 0x3fb8aa3b, v15
	v_mul_f32_e32 v0, 0x3fb8aa3b, v0
	v_exp_f32_e32 v23, v14
	v_exp_f32_e32 v22, v0
	v_and_b32_e32 v14, 0xffff0000, v19
	v_mul_f32_e32 v0, v13, v17
	v_mul_f32_e32 v13, v0, v14
	v_lshlrev_b64 v[14:15], 2, v[20:21]
	v_mul_f32_e32 v10, v10, v16
	v_lshl_add_u64 v[16:17], v[142:143], 0, v[14:15]
	v_lshl_add_u64 v[14:15], v[144:145], 0, v[14:15]
	global_store_dwordx4 v[16:17], v[22:25], off
	global_store_dwordx4 v[14:15], v[10:13], off

.LBB0_455:
	s_or_b64 exec, exec, s[26:27]
	s_waitcnt vmcnt(1) lgkmcnt(0)
	v_add_f32_e32 v12, v8, v12
	v_mul_f32_e32 v12, 0xbfb8aa3b, v12
	v_exp_f32_e32 v12, v12
	v_add_f32_e32 v13, v9, v13
	v_mul_f32_e32 v13, 0xbfb8aa3b, v13
	v_exp_f32_e32 v13, v13
	v_add_f32_e32 v12, 1.0, v12
	v_add_f32_e32 v13, 1.0, v13
	v_rcp_f32_e32 v12, v12
	s_nop 2
	v_add_f32_e32 v11, v7, v11
	v_mul_f32_e32 v11, 0xbfb8aa3b, v11
	v_mul_f32_e32 v12, v12, v24
	s_nop 0
	v_exp_f32_e32 v11, v11
	s_waitcnt vmcnt(0)
	v_lshlrev_b32_e32 v28, 16, v19
	s_nop 1
	v_mul_f32_e32 v12, v12, v28
	s_nop 2
	v_add_f32_e32 v11, 1.0, v11
	s_nop 3
	v_rcp_f32_e32 v13, v13
	s_nop 0
	v_mul_f32_e32 v24, 0x3fb8aa3b, v25
	v_exp_f32_e32 v25, v24
	s_nop 2
	v_add_f32_e32 v10, v6, v10
	s_nop 0
	v_mul_f32_e32 v10, 0xbfb8aa3b, v10
	s_nop 0
	v_exp_f32_e32 v10, v10
	s_nop 2
	v_rcp_f32_e32 v11, v11
	s_nop 0
	v_add_f32_e32 v10, 1.0, v10
	v_mul_f32_e32 v11, v11, v23
	s_nop 1
	v_and_b32_e32 v24, 0xffff0000, v18
	v_mul_f32_e32 v16, 0x3fb8aa3b, v16
	v_mul_f32_e32 v11, v11, v24
	v_exp_f32_e32 v24, v16
	v_lshlrev_b32_e32 v16, 16, v18
	s_nop 7
	v_rcp_f32_e32 v10, v10
	s_nop 0
	v_mul_f32_e32 v15, 0x3fb8aa3b, v15
	v_mul_f32_e32 v14, 0x3fb8aa3b, v14
	v_mul_f32_e32 v10, v10, v22
	v_exp_f32_e32 v23, v15
	v_exp_f32_e32 v22, v14
	v_and_b32_e32 v15, 0xffff0000, v19
	v_mul_f32_e32 v13, v13, v17
	v_mul_f32_e32 v13, v13, v15
	v_lshlrev_b64 v[14:15], 2, v[20:21]
	v_mul_f32_e32 v10, v10, v16
	v_lshl_add_u64 v[16:17], v[142:143], 0, v[14:15]
	v_lshl_add_u64 v[14:15], v[144:145], 0, v[14:15]
	global_store_dwordx4 v[16:17], v[22:25], off
	global_store_dwordx4 v[14:15], v[10:13], off

.LBB0_1141:
	s_andn2_saveexec_b64 s[12:13], s[12:13]
	s_cbranch_execz .LBB0_1143
	v_mul_f32_e32 v2, 0xbfb8aa3b, v2
	v_exp_f32_e32 v2, v2
	s_nop 0
	v_add_f32_e32 v2, 1.0, v2
	s_nop 7
	s_nop 2
	v_mov_b32_e32 v37, v1
	v_rcp_f32_e32 v2, v2
	s_nop 0
	v_lshl_add_u64 v[36:37], s[6:7], 0, v[36:37]
	v_cvt_pk_bf16_f32 v2, v2, s0
	v_lshl_add_u64 v[36:37], v[18:19], 1, v[36:37]
	global_store_short v[36:37], v2, off
